# softmax loops: persistent -m splat as MFMA C operand (diff maps), dropped redundant canonicalizing max, shortened common-path branch chain
# speedup vs baseline: 1.0540x; 1.0098x over previous
.LBB0_132:
	s_and_b32 s5, s64, 7
	s_lshl_b32 s0, s5, 8
	s_or_b32 s22, s14, s0
	s_mov_b32 s23, s15
	s_lshl_b64 s[0:1], s[22:23], 10
	s_add_u32 s0, s55, s0
	s_addc_u32 s1, s56, s1
	s_lshl_b32 s4, s64, 4
	s_and_b32 s65, s4, 0x180
	s_lshl_b32 s4, s65, 1
	s_add_u32 s30, s0, s4
	s_addc_u32 s31, s1, 0
	s_lshl_b64 s[0:1], s[2:3], 21
	s_add_u32 s3, s57, s0
	s_addc_u32 s6, s58, s1
	s_add_u32 s24, s3, s4
	s_addc_u32 s25, s6, 0
	v_mov_b32_e32 v121, v218
	s_add_u32 s0, s90, s0
	v_mov_b32_e32 v4, v218
	s_addc_u32 s1, s91, s1
	s_add_u32 s3, s0, s4
	v_ashrrev_i32_e32 v0, 6, v4
	v_and_b32_e32 v6, 31, v4
	v_readfirstlane_b32 s0, v0
	v_lshl_or_b32 v0, v0, 5, v6
	v_ashrrev_i32_e32 v1, 31, v0
	v_lshlrev_b64 v[0:1], 10, v[0:1]
	v_lshrrev_b32_e32 v7, 1, v4
	v_and_b32_e32 v5, 63, v4
	v_lshl_add_u64 v[0:1], s[30:31], 0, v[0:1]
	v_and_b32_e32 v184, 16, v7
	s_addc_u32 s66, s1, 0
	v_lshl_add_u64 v[0:1], v[0:1], 0, v[184:185]
	s_lshl_b32 s1, s0, 10
	v_lshlrev_b32_e32 v8, 4, v5
	flat_load_dwordx4 v[96:99], v[0:1]
	flat_load_dwordx4 v[100:103], v[0:1] offset:32
	flat_load_dwordx4 v[104:107], v[0:1] offset:64
	flat_load_dwordx4 v[108:111], v[0:1] offset:96
	v_or_b32_e32 v0, s1, v8
	v_ashrrev_i32_e32 v1, 31, v0
	v_lshrrev_b32_e32 v1, 25, v1
	v_add_u32_e32 v1, v0, v1
	v_lshlrev_b32_e32 v9, 3, v5
	s_lshl_b32 s0, s0, 6
	v_ashrrev_i32_e32 v2, 7, v1
	v_and_b32_e32 v1, 0xffffff80, v1
	v_and_b32_e32 v3, 32, v4
	s_and_b32 s0, s0, 64
	v_and_b32_e32 v10, 24, v9
	v_sub_u32_e32 v0, v0, v1
	v_or3_b32 v3, v10, v3, s0
	s_ashr_i32 s0, s1, 8
	v_ashrrev_i32_e32 v0, 4, v0
	v_lshrrev_b32_e32 v1, 1, v2
	s_and_b32 s6, s0, 0x7ffff0
	s_lshr_b32 s0, s0, 1
	v_bitop3_b32 v0, v1, v0, 7 bitop3:0x6c
	v_bfe_u32 v1, v4, 2, 2
	s_and_b32 s0, s0, 4
	v_and_or_b32 v1, v7, 8, v1
	s_or_b32 s0, s6, s0
	v_or_b32_e32 v10, s0, v1
	s_add_i32 s0, s1, 0x2000
	s_ashr_i32 s0, s0, 8
	s_and_b32 s6, s0, 0x7ffff0
	s_lshr_b32 s0, s0, 1
	s_and_b32 s0, s0, 4
	s_or_b32 s0, s6, s0
	s_add_i32 s4, 0, 0x14000
	v_or_b32_e32 v1, s0, v1
	s_lshl_b32 s0, s5, 17
	s_lshl_b32 s6, s5, 18
	v_lshl_or_b32 v114, v1, 9, v3
	v_lshlrev_b32_e32 v1, 9, v2
	s_add_u32 s68, s24, s6
	v_lshl_add_u32 v0, v0, 3, v1
	s_addc_u32 s69, s25, 0
	s_add_i32 s5, s1, 0
	v_ashrrev_i32_e32 v1, 31, v0
	s_add_i32 m0, s5, 0x8000
	v_lshl_or_b32 v112, v10, 9, v3
	v_lshlrev_b64 v[0:1], 1, v[0:1]
	s_add_u32 s34, s3, s6
	v_lshl_add_u64 v[2:3], s[68:69], 0, v[0:1]
	s_addc_u32 s35, s66, 0
	v_ashrrev_i32_e32 v113, 31, v112
	s_waitcnt lgkmcnt(0)
	s_barrier
	global_load_lds_dwordx4 v[2:3], off
	v_lshl_add_u64 v[2:3], v[112:113], 1, s[34:35]
	s_mov_b32 m0, s5
	v_ashrrev_i32_e32 v115, 31, v114
	global_load_lds_dwordx4 v[2:3], off
	v_lshl_add_u64 v[2:3], v[114:115], 1, s[34:35]
	s_add_i32 m0, s5, 0x2000
	s_cmp_lg_u32 0, -1
	global_load_lds_dwordx4 v[2:3], off
	v_and_b32_e32 v2, 0x3fffffc0, v4
	v_lshl_add_u32 v119, v2, 2, s4
	v_lshlrev_b32_e32 v2, 1, v4
	s_cselect_b32 s1, 0, 0
	v_and_b32_e32 v2, 32, v2
	v_lshlrev_b32_e32 v4, 3, v4
	s_add_i32 s6, s1, 0x8000
	s_movk_i32 s54, 0x118
	v_and_b32_e32 v3, 0xc0, v8
	s_waitcnt vmcnt(0)
	v_and_b32_e32 v4, 0x70, v4
	v_lshl_add_u32 v120, v6, 7, s6
	s_movk_i32 s6, 0x60
	v_lshl_add_u64 v[116:117], s[24:25], 0, v[0:1]
	v_and_or_b32 v0, v9, s54, v2
	v_mov_b32_e32 v14, v185
	v_mov_b32_e32 v15, v185
	v_bitop3_b32 v123, v7, v4, 16 bitop3:0x6c
	v_bitop3_b32 v124, v184, v4, 32 bitop3:0x36
	v_bitop3_b32 v125, v184, v4, 64 bitop3:0x36
	v_bitop3_b32 v126, v184, v4, s6 bitop3:0x36
	v_cmp_gt_u32_e64 s[6:7], 32, v5
	v_lshl_add_u32 v122, v6, 2, v119
	v_add3_u32 v127, v3, s1, v0
	s_or_b32 s67, s0, 0x8000
	v_mov_b32_e32 v0, v185
	v_mov_b32_e32 v1, v185
	v_mov_b32_e32 v2, v185
	v_mov_b32_e32 v3, v185
	v_mov_b32_e32 v4, v185
	v_mov_b32_e32 v5, v185
	v_mov_b32_e32 v6, v185
	v_mov_b32_e32 v7, v185
	v_mov_b32_e32 v8, v185
	v_mov_b32_e32 v9, v185
	v_mov_b32_e32 v10, v185
	v_mov_b32_e32 v11, v185
	v_mov_b32_e32 v12, v185
	v_mov_b32_e32 v13, v185
	v_mov_b64_e32 v[30:31], v[14:15]
	v_mov_b64_e32 v[46:47], v[14:15]
	v_mov_b64_e32 v[62:63], v[14:15]
	s_mov_b32 s53, 0
	v_mov_b32_e32 v128, 0
	v_mov_b32_e32 v160, 0x80000000
	v_mov_b32_e32 v161, 0x80000000
	v_mov_b32_e32 v162, 0x80000000
	v_mov_b32_e32 v163, 0x80000000
	v_mov_b32_e32 v164, 0x80000000
	v_mov_b32_e32 v165, 0x80000000
	v_mov_b32_e32 v166, 0x80000000
	v_mov_b32_e32 v167, 0x80000000
	v_mov_b32_e32 v168, 0x80000000
	v_mov_b32_e32 v169, 0x80000000
	v_mov_b32_e32 v170, 0x80000000
	v_mov_b32_e32 v171, 0x80000000
	v_mov_b32_e32 v172, 0x80000000
	v_mov_b32_e32 v173, 0x80000000
	v_mov_b32_e32 v174, 0x80000000
	v_mov_b32_e32 v175, 0x80000000
	s_mov_b32 s54, s67
	v_mov_b64_e32 v[28:29], v[12:13]
	v_mov_b64_e32 v[26:27], v[10:11]
	v_mov_b64_e32 v[24:25], v[8:9]
	v_mov_b64_e32 v[22:23], v[6:7]
	v_mov_b64_e32 v[20:21], v[4:5]
	v_mov_b64_e32 v[18:19], v[2:3]
	v_mov_b64_e32 v[16:17], v[0:1]
	v_mov_b64_e32 v[44:45], v[12:13]
	v_mov_b64_e32 v[42:43], v[10:11]
	v_mov_b64_e32 v[40:41], v[8:9]
	v_mov_b64_e32 v[38:39], v[6:7]
	v_mov_b64_e32 v[36:37], v[4:5]
	v_mov_b64_e32 v[34:35], v[2:3]
	v_mov_b64_e32 v[32:33], v[0:1]
	v_mov_b64_e32 v[60:61], v[12:13]
	v_mov_b64_e32 v[58:59], v[10:11]
	v_mov_b64_e32 v[56:57], v[8:9]
	v_mov_b64_e32 v[54:55], v[6:7]
	v_mov_b64_e32 v[52:53], v[4:5]
	v_mov_b64_e32 v[50:51], v[2:3]
	v_mov_b64_e32 v[48:49], v[0:1]
	v_mov_b32_e32 v129, 0
	s_waitcnt vmcnt(0) lgkmcnt(0)
	s_barrier
	s_and_b32 s80, s53, 1
	s_cmp_eq_u32 s53, 31
	s_movk_i32 s0, 0x2000
	s_cbranch_scc1 .LBB0_134

.LBB0_134:
	v_add_u32_e32 v80, s0, v120
	v_add_u32_e32 v81, v80, v123
	ds_read_b128 v[130:133], v81 offset:0
	ds_read_b128 v[134:137], v81 offset:0x1000
	v_add_u32_e32 v82, v80, v124
	ds_read_b128 v[138:141], v82 offset:0
	ds_read_b128 v[146:149], v82 offset:0x1000
	s_waitcnt lgkmcnt(2)
	v_add_u32_e32 v118, v80, v125
	v_add_u32_e32 v142, v80, v126
	v_mfma_f32_32x32x16_bf16 v[80:95], v[130:133], v[96:99], v[160:175]
	ds_read_b128 v[130:133], v118 offset:0
	v_mfma_f32_32x32x16_bf16 v[64:79], v[134:137], v[96:99], v[160:175]
	ds_read_b128 v[134:137], v118 offset:0x1000
	s_waitcnt lgkmcnt(2)
	v_mfma_f32_32x32x16_bf16 v[80:95], v[138:141], v[100:103], v[80:95]
	ds_read_b128 v[138:141], v142 offset:0
	v_mfma_f32_32x32x16_bf16 v[64:79], v[146:149], v[100:103], v[64:79]
	ds_read_b128 v[146:149], v142 offset:0x1000
	s_waitcnt lgkmcnt(2)
	v_mfma_f32_32x32x16_bf16 v[80:95], v[130:133], v[104:107], v[80:95]
	s_waitcnt lgkmcnt(0)
	v_mfma_f32_32x32x16_bf16 v[64:79], v[134:137], v[104:107], v[64:79]
	v_mfma_f32_32x32x16_bf16 v[80:95], v[138:141], v[108:111], v[80:95]
	s_cmp_eq_u32 s53, 0
	s_cselect_b64 s[70:71], -1, 0
	s_cmp_lg_u32 s53, 0
	v_mfma_f32_32x32x16_bf16 v[64:79], v[146:149], v[108:111], v[64:79]
	s_nop 7
	v_max_f32_e32 v118, v80, v81
	v_max3_f32 v118, v118, v82, v83
	v_max3_f32 v118, v118, v84, v85
	v_max3_f32 v118, v118, v86, v87
	v_max3_f32 v118, v118, v88, v89
	v_max3_f32 v118, v118, v90, v91
	v_max3_f32 v118, v118, v92, v93
	v_max3_f32 v118, v118, v94, v95
	v_max3_f32 v118, v118, v64, v65
	v_max3_f32 v118, v118, v66, v67
	v_max3_f32 v118, v118, v68, v69
	v_max3_f32 v118, v118, v70, v71
	v_max3_f32 v118, v118, v72, v73
	v_max3_f32 v118, v118, v74, v75
	v_max3_f32 v118, v118, v76, v77
	v_max3_f32 v118, v118, v78, v79
	v_mov_b32_e32 v130, v118
	s_nop 1
	v_permlane32_swap_b32_e32 v118, v130
	v_max_f32_e32 v130, v118, v130
	s_cbranch_scc0 .LBB0_139
	v_cmp_ge_f32_e32 vcc, s62, v130
	s_cmp_lg_u64 vcc, exec
	s_mov_b64 s[74:75], 0
	s_mov_b64 s[72:73], 0
	s_cbranch_scc1 .LBB0_140
	v_mov_b32_e32 v130, 1.0
	s_branch .LBB0_146

.LBB0_142:
	v_exp_f32_e64 v130, -v118
	v_add_f32_e32 v128, v128, v118
	v_xor_b32_e32 v160, 0x80000000, v128
	v_mov_b32_e32 v161, v160
	v_mov_b32_e32 v162, v160
	v_mov_b32_e32 v163, v160
	v_mov_b32_e32 v164, v160
	v_mov_b32_e32 v165, v160
	v_mov_b32_e32 v166, v160
	v_mov_b32_e32 v167, v160
	v_mov_b32_e32 v168, v160
	v_mov_b32_e32 v169, v160
	v_mov_b32_e32 v170, v160
	v_mov_b32_e32 v171, v160
	v_mov_b32_e32 v172, v160
	v_mov_b32_e32 v173, v160
	v_mov_b32_e32 v174, v160
	v_mov_b32_e32 v175, v160
	v_pk_add_f32 v[80:81], v[80:81], v[118:119] op_sel_hi:[1,0] neg_lo:[0,1] neg_hi:[0,1]
	v_pk_add_f32 v[82:83], v[82:83], v[118:119] op_sel_hi:[1,0] neg_lo:[0,1] neg_hi:[0,1]
	v_cndmask_b32_e64 v130, v130, 0, s[70:71]
	v_pk_add_f32 v[84:85], v[84:85], v[118:119] op_sel_hi:[1,0] neg_lo:[0,1] neg_hi:[0,1]
	v_pk_add_f32 v[86:87], v[86:87], v[118:119] op_sel_hi:[1,0] neg_lo:[0,1] neg_hi:[0,1]
	v_pk_add_f32 v[88:89], v[88:89], v[118:119] op_sel_hi:[1,0] neg_lo:[0,1] neg_hi:[0,1]
	v_pk_add_f32 v[90:91], v[90:91], v[118:119] op_sel_hi:[1,0] neg_lo:[0,1] neg_hi:[0,1]
	v_pk_add_f32 v[92:93], v[92:93], v[118:119] op_sel_hi:[1,0] neg_lo:[0,1] neg_hi:[0,1]
	v_pk_add_f32 v[94:95], v[94:95], v[118:119] op_sel_hi:[1,0] neg_lo:[0,1] neg_hi:[0,1]
	v_sub_f32_e32 v79, v79, v118
	v_sub_f32_e32 v78, v78, v118
	v_sub_f32_e32 v77, v77, v118
	v_sub_f32_e32 v76, v76, v118
	v_sub_f32_e32 v75, v75, v118
	v_sub_f32_e32 v74, v74, v118
	v_sub_f32_e32 v73, v73, v118
	v_sub_f32_e32 v72, v72, v118
	v_sub_f32_e32 v71, v71, v118
	v_sub_f32_e32 v70, v70, v118
	v_sub_f32_e32 v69, v69, v118
	v_sub_f32_e32 v68, v68, v118
	v_sub_f32_e32 v67, v67, v118
	v_sub_f32_e32 v66, v66, v118
	v_sub_f32_e32 v65, v65, v118
	v_sub_f32_e32 v64, v64, v118
	v_cmp_gt_f32_e32 vcc, 1.0, v130
	s_cbranch_vccz .LBB0_146

.LBB0_148:
	s_and_saveexec_b64 s[0:1], s[6:7]
	ds_write_b32 v122, v64
	s_or_b64 exec, exec, s[0:1]
	v_lshlrev_b32_e32 v64, 6, v121
	v_ashrrev_i32_e32 v65, 31, v64
	s_waitcnt lgkmcnt(0)
	v_add_u32_e32 v80, v119, v184
	v_lshl_add_u64 v[112:113], v[64:65], 2, s[12:13]
	ds_read_b128 v[64:67], v80
	ds_read_b128 v[68:71], v80 offset:32
	s_mov_b32 s5, 0
	v_mov_b32_e32 v130, 0
	v_mov_b32_e32 v131, 0
	s_waitcnt lgkmcnt(1)
	v_rcp_f32_e32 v72, v64
	v_rcp_f32_e32 v73, v65
	v_rcp_f32_e32 v74, v66
	v_rcp_f32_e32 v75, v67
	ds_read_b128 v[64:67], v80 offset:64
	s_waitcnt lgkmcnt(1)
	v_rcp_f32_e32 v68, v68
	v_rcp_f32_e32 v69, v69
	v_rcp_f32_e32 v70, v70
	v_rcp_f32_e32 v71, v71
	s_waitcnt lgkmcnt(0)
	v_rcp_f32_e32 v76, v64
	v_rcp_f32_e32 v77, v65
	v_rcp_f32_e32 v78, v66
	v_rcp_f32_e32 v79, v67
	ds_read_b128 v[64:67], v80 offset:96
	v_pk_mul_f32 v[48:49], v[48:49], v[72:73]
	v_pk_mul_f32 v[50:51], v[50:51], v[74:75]
	v_pk_mul_f32 v[32:33], v[32:33], v[72:73]
	v_pk_mul_f32 v[34:35], v[34:35], v[74:75]
	s_waitcnt lgkmcnt(0)
	v_rcp_f32_e32 v64, v64
	v_rcp_f32_e32 v65, v65
	v_rcp_f32_e32 v66, v66
	v_rcp_f32_e32 v67, v67
	v_pk_mul_f32 v[16:17], v[16:17], v[72:73]
	v_pk_mul_f32 v[18:19], v[18:19], v[74:75]
	v_pk_mul_f32 v[0:1], v[0:1], v[72:73]
	v_pk_mul_f32 v[2:3], v[2:3], v[74:75]
	flat_store_dwordx4 v[112:113], v[48:51]
	flat_store_dwordx4 v[112:113], v[32:35] offset:64
	flat_store_dwordx4 v[112:113], v[16:19] offset:128
	v_pk_mul_f32 v[48:49], v[52:53], v[68:69]
	v_pk_mul_f32 v[50:51], v[54:55], v[70:71]
	v_pk_mul_f32 v[32:33], v[36:37], v[68:69]
	v_pk_mul_f32 v[34:35], v[38:39], v[70:71]
	v_pk_mul_f32 v[16:17], v[20:21], v[68:69]
	v_pk_mul_f32 v[18:19], v[22:23], v[70:71]
	flat_store_dwordx4 v[112:113], v[0:3] offset:192
	flat_store_dwordx4 v[112:113], v[48:51] offset:16
	flat_store_dwordx4 v[112:113], v[32:35] offset:80
	v_pk_mul_f32 v[0:1], v[4:5], v[68:69]
	v_pk_mul_f32 v[2:3], v[6:7], v[70:71]
	v_pk_mul_f32 v[48:49], v[56:57], v[76:77]
	v_pk_mul_f32 v[50:51], v[58:59], v[78:79]
	v_pk_mul_f32 v[32:33], v[40:41], v[76:77]
	v_pk_mul_f32 v[34:35], v[42:43], v[78:79]
	flat_store_dwordx4 v[112:113], v[16:19] offset:144
	flat_store_dwordx4 v[112:113], v[0:3] offset:208
	flat_store_dwordx4 v[112:113], v[48:51] offset:32
	v_pk_mul_f32 v[16:17], v[24:25], v[76:77]
	v_pk_mul_f32 v[18:19], v[26:27], v[78:79]
	v_pk_mul_f32 v[0:1], v[8:9], v[76:77]
	v_pk_mul_f32 v[2:3], v[10:11], v[78:79]
	v_pk_mul_f32 v[48:49], v[60:61], v[64:65]
	v_pk_mul_f32 v[50:51], v[62:63], v[66:67]
	flat_store_dwordx4 v[112:113], v[32:35] offset:96
	flat_store_dwordx4 v[112:113], v[16:19] offset:160
	flat_store_dwordx4 v[112:113], v[0:3] offset:224
	v_pk_mul_f32 v[32:33], v[44:45], v[64:65]
	v_pk_mul_f32 v[34:35], v[46:47], v[66:67]
	v_pk_mul_f32 v[16:17], v[28:29], v[64:65]
	v_pk_mul_f32 v[18:19], v[30:31], v[66:67]
	v_pk_mul_f32 v[0:1], v[12:13], v[64:65]
	v_pk_mul_f32 v[2:3], v[14:15], v[66:67]
	v_mov_b32_e32 v4, v218
	flat_store_dwordx4 v[112:113], v[48:51] offset:48
	flat_store_dwordx4 v[112:113], v[32:35] offset:112
	flat_store_dwordx4 v[112:113], v[16:19] offset:176
	flat_store_dwordx4 v[112:113], v[0:3] offset:240
	v_mov_b32_e32 v14, v185
	v_and_b32_e32 v6, 31, v4
	v_and_b32_e32 v0, 0x3fffffc0, v4
	v_lshl_add_u32 v122, v0, 2, s4
	v_ashrrev_i32_e32 v0, 6, v4
	v_lshrrev_b32_e32 v7, 1, v4
	v_readfirstlane_b32 s0, v0
	v_lshl_or_b32 v0, v0, 5, v6
	v_ashrrev_i32_e32 v1, 31, v0
	v_lshlrev_b64 v[0:1], 10, v[0:1]
	v_and_b32_e32 v5, 63, v4
	v_lshl_add_u64 v[0:1], s[30:31], 0, v[0:1]
	v_and_b32_e32 v184, 16, v7
	v_lshl_add_u64 v[0:1], v[0:1], 0, v[184:185]
	s_lshl_b32 s1, s0, 10
	v_lshlrev_b32_e32 v8, 4, v5
	flat_load_dwordx4 v[96:99], v[0:1] offset:128
	flat_load_dwordx4 v[100:103], v[0:1] offset:160
	flat_load_dwordx4 v[104:107], v[0:1] offset:192
	flat_load_dwordx4 v[108:111], v[0:1] offset:224
	v_or_b32_e32 v0, s1, v8
	v_ashrrev_i32_e32 v1, 31, v0
	v_lshrrev_b32_e32 v1, 25, v1
	v_add_u32_e32 v1, v0, v1
	v_lshlrev_b32_e32 v9, 3, v5
	s_lshl_b32 s0, s0, 6
	v_ashrrev_i32_e32 v2, 7, v1
	v_and_b32_e32 v1, 0xffffff80, v1
	v_and_b32_e32 v3, 32, v4
	s_and_b32 s0, s0, 64
	v_and_b32_e32 v10, 24, v9
	v_sub_u32_e32 v0, v0, v1
	v_or3_b32 v3, v10, v3, s0
	s_ashr_i32 s0, s1, 8
	v_ashrrev_i32_e32 v0, 4, v0
	v_lshrrev_b32_e32 v1, 1, v2
	s_and_b32 s4, s0, 0x7ffff0
	s_lshr_b32 s0, s0, 1
	v_bitop3_b32 v0, v1, v0, 7 bitop3:0x6c
	v_bfe_u32 v1, v4, 2, 2
	s_and_b32 s0, s0, 4
	v_and_or_b32 v1, v7, 8, v1
	s_or_b32 s0, s4, s0
	v_or_b32_e32 v10, s0, v1
	s_add_i32 s0, s1, 0x2000
	s_ashr_i32 s0, s0, 8
	s_and_b32 s4, s0, 0x7ffff0
	s_lshr_b32 s0, s0, 1
	s_and_b32 s0, s0, 4
	s_or_b32 s0, s4, s0
	v_or_b32_e32 v1, s0, v1
	v_lshl_or_b32 v116, v1, 9, v3
	v_lshlrev_b32_e32 v1, 9, v2
	v_lshl_add_u32 v0, v0, 3, v1
	v_ashrrev_i32_e32 v1, 31, v0
	v_lshlrev_b64 v[0:1], 1, v[0:1]
	v_lshl_or_b32 v114, v10, 9, v3
	v_lshl_add_u64 v[2:3], s[68:69], 0, v[0:1]
	s_add_i32 s4, s1, 0
	v_lshl_add_u64 v[2:3], v[2:3], 0, s[78:79]
	s_add_i32 m0, s4, 0x8000
	v_ashrrev_i32_e32 v115, 31, v114
	s_waitcnt lgkmcnt(0)
	s_barrier
	global_load_lds_dwordx4 v[2:3], off
	v_lshl_add_u64 v[2:3], v[114:115], 1, s[34:35]
	s_mov_b32 m0, s4
	v_ashrrev_i32_e32 v117, 31, v116
	global_load_lds_dwordx4 v[2:3], off
	v_lshl_add_u64 v[2:3], v[116:117], 1, s[34:35]
	s_add_i32 m0, s4, 0x2000
	s_cmp_lg_u32 0, -1
	global_load_lds_dwordx4 v[2:3], off
	s_cselect_b32 s0, 0, 0
	v_lshlrev_b32_e32 v10, 1, v4
	v_lshlrev_b32_e32 v4, 3, v4
	s_add_i32 s1, s0, 0x8000
	v_and_b32_e32 v4, 0x70, v4
	v_lshl_add_u32 v124, v6, 7, s1
	s_movk_i32 s1, 0x60
	v_and_b32_e32 v3, 32, v10
	v_bitop3_b32 v128, v184, v4, s1 bitop3:0x36
	s_movk_i32 s1, 0x118
	v_and_b32_e32 v2, 0xc0, v8
	s_waitcnt vmcnt(0)
	v_lshl_add_u64 v[118:119], s[24:25], 0, v[0:1]
	v_and_or_b32 v0, v9, s1, v3
	v_mov_b32_e32 v15, v185
	v_bitop3_b32 v125, v7, v4, 16 bitop3:0x6c
	v_bitop3_b32 v126, v184, v4, 32 bitop3:0x36
	v_bitop3_b32 v127, v184, v4, 64 bitop3:0x36
	v_cmp_gt_u32_e64 s[6:7], 32, v5
	v_lshl_add_u32 v123, v6, 2, v122
	v_add3_u32 v129, v2, s0, v0
	v_mov_b32_e32 v0, v185
	v_mov_b32_e32 v1, v185
	v_mov_b32_e32 v2, v185
	v_mov_b32_e32 v3, v185
	v_mov_b32_e32 v4, v185
	v_mov_b32_e32 v5, v185
	v_mov_b32_e32 v6, v185
	v_mov_b32_e32 v7, v185
	v_mov_b32_e32 v8, v185
	v_mov_b32_e32 v9, v185
	v_mov_b32_e32 v10, v185
	v_mov_b32_e32 v11, v185
	v_mov_b32_e32 v12, v185
	v_mov_b32_e32 v13, v185
	v_mov_b64_e32 v[30:31], v[14:15]
	v_mov_b64_e32 v[46:47], v[14:15]
	v_mov_b64_e32 v[62:63], v[14:15]
	v_mov_b64_e32 v[28:29], v[12:13]
	v_mov_b64_e32 v[26:27], v[10:11]
	v_mov_b64_e32 v[24:25], v[8:9]
	v_mov_b64_e32 v[22:23], v[6:7]
	v_mov_b64_e32 v[20:21], v[4:5]
	v_mov_b64_e32 v[18:19], v[2:3]
	v_mov_b64_e32 v[16:17], v[0:1]
	v_mov_b64_e32 v[44:45], v[12:13]
	v_mov_b64_e32 v[42:43], v[10:11]
	v_mov_b64_e32 v[40:41], v[8:9]
	v_mov_b64_e32 v[38:39], v[6:7]
	v_mov_b64_e32 v[36:37], v[4:5]
	v_mov_b64_e32 v[34:35], v[2:3]
	v_mov_b64_e32 v[32:33], v[0:1]
	v_mov_b64_e32 v[60:61], v[12:13]
	v_mov_b64_e32 v[58:59], v[10:11]
	v_mov_b64_e32 v[56:57], v[8:9]
	v_mov_b64_e32 v[54:55], v[6:7]
	v_mov_b64_e32 v[52:53], v[4:5]
	v_mov_b64_e32 v[50:51], v[2:3]
	v_mov_b64_e32 v[48:49], v[0:1]
	v_mov_b32_e32 v160, 0x80000000
	v_mov_b32_e32 v161, 0x80000000
	v_mov_b32_e32 v162, 0x80000000
	v_mov_b32_e32 v163, 0x80000000
	v_mov_b32_e32 v164, 0x80000000
	v_mov_b32_e32 v165, 0x80000000
	v_mov_b32_e32 v166, 0x80000000
	v_mov_b32_e32 v167, 0x80000000
	v_mov_b32_e32 v168, 0x80000000
	v_mov_b32_e32 v169, 0x80000000
	v_mov_b32_e32 v170, 0x80000000
	v_mov_b32_e32 v171, 0x80000000
	v_mov_b32_e32 v172, 0x80000000
	v_mov_b32_e32 v173, 0x80000000
	v_mov_b32_e32 v174, 0x80000000
	v_mov_b32_e32 v175, 0x80000000
	v_readlane_b32 s54, v254, 48
	s_waitcnt vmcnt(0) lgkmcnt(0)
	s_barrier
	s_and_b32 s53, s5, 1
	s_cmp_eq_u32 s5, 31
	s_movk_i32 s0, 0x2000
	s_cbranch_scc1 .LBB0_152

.LBB0_152:
	v_add_u32_e32 v80, s0, v124
	v_add_u32_e32 v81, v80, v125
	ds_read_b128 v[132:135], v81 offset:0
	ds_read_b128 v[136:139], v81 offset:0x1000
	v_add_u32_e32 v82, v80, v126
	ds_read_b128 v[140:143], v82 offset:0
	ds_read_b128 v[146:149], v82 offset:0x1000
	s_waitcnt lgkmcnt(2)
	v_add_u32_e32 v120, v80, v127
	v_add_u32_e32 v150, v80, v128
	v_mfma_f32_32x32x16_bf16 v[80:95], v[132:135], v[96:99], v[160:175]
	ds_read_b128 v[132:135], v120 offset:0
	v_mfma_f32_32x32x16_bf16 v[64:79], v[136:139], v[96:99], v[160:175]
	ds_read_b128 v[136:139], v120 offset:0x1000
	s_waitcnt lgkmcnt(2)
	v_mfma_f32_32x32x16_bf16 v[80:95], v[140:143], v[100:103], v[80:95]
	ds_read_b128 v[140:143], v150 offset:0
	v_mfma_f32_32x32x16_bf16 v[64:79], v[146:149], v[100:103], v[64:79]
	ds_read_b128 v[146:149], v150 offset:0x1000
	s_waitcnt lgkmcnt(2)
	v_mfma_f32_32x32x16_bf16 v[80:95], v[132:135], v[104:107], v[80:95]
	s_waitcnt lgkmcnt(0)
	v_mfma_f32_32x32x16_bf16 v[64:79], v[136:139], v[104:107], v[64:79]
	v_mfma_f32_32x32x16_bf16 v[80:95], v[140:143], v[108:111], v[80:95]
	s_cmp_eq_u32 s5, 0
	s_cselect_b64 s[24:25], -1, 0
	s_cmp_lg_u32 s5, 0
	v_mfma_f32_32x32x16_bf16 v[64:79], v[146:149], v[108:111], v[64:79]
	s_nop 7
	v_max_f32_e32 v120, v80, v81
	v_max3_f32 v120, v120, v82, v83
	v_max3_f32 v120, v120, v84, v85
	v_max3_f32 v120, v120, v86, v87
	v_max3_f32 v120, v120, v88, v89
	v_max3_f32 v120, v120, v90, v91
	v_max3_f32 v120, v120, v92, v93
	v_max3_f32 v120, v120, v94, v95
	v_max3_f32 v120, v120, v64, v65
	v_max3_f32 v120, v120, v66, v67
	v_max3_f32 v120, v120, v68, v69
	v_max3_f32 v120, v120, v70, v71
	v_max3_f32 v120, v120, v72, v73
	v_max3_f32 v120, v120, v74, v75
	v_max3_f32 v120, v120, v76, v77
	v_max3_f32 v120, v120, v78, v79
	v_mov_b32_e32 v132, v120
	s_nop 1
	v_permlane32_swap_b32_e32 v120, v132
	v_max_f32_e32 v132, v120, v132
	s_cbranch_scc0 .LBB0_157
	v_cmp_ge_f32_e32 vcc, s62, v132
	s_cmp_lg_u64 vcc, exec
	s_mov_b64 s[34:35], 0
	s_mov_b64 s[30:31], 0
	s_cbranch_scc1 .LBB0_158
	v_mov_b32_e32 v132, 1.0
	s_branch .LBB0_164

.LBB0_160:
	v_exp_f32_e64 v132, -v120
	v_add_f32_e32 v130, v130, v120
	v_xor_b32_e32 v160, 0x80000000, v130
	v_mov_b32_e32 v161, v160
	v_mov_b32_e32 v162, v160
	v_mov_b32_e32 v163, v160
	v_mov_b32_e32 v164, v160
	v_mov_b32_e32 v165, v160
	v_mov_b32_e32 v166, v160
	v_mov_b32_e32 v167, v160
	v_mov_b32_e32 v168, v160
	v_mov_b32_e32 v169, v160
	v_mov_b32_e32 v170, v160
	v_mov_b32_e32 v171, v160
	v_mov_b32_e32 v172, v160
	v_mov_b32_e32 v173, v160
	v_mov_b32_e32 v174, v160
	v_mov_b32_e32 v175, v160
	v_pk_add_f32 v[80:81], v[80:81], v[120:121] op_sel_hi:[1,0] neg_lo:[0,1] neg_hi:[0,1]
	v_pk_add_f32 v[82:83], v[82:83], v[120:121] op_sel_hi:[1,0] neg_lo:[0,1] neg_hi:[0,1]
	v_cndmask_b32_e64 v132, v132, 0, s[24:25]
	v_pk_add_f32 v[84:85], v[84:85], v[120:121] op_sel_hi:[1,0] neg_lo:[0,1] neg_hi:[0,1]
	v_pk_add_f32 v[86:87], v[86:87], v[120:121] op_sel_hi:[1,0] neg_lo:[0,1] neg_hi:[0,1]
	v_pk_add_f32 v[88:89], v[88:89], v[120:121] op_sel_hi:[1,0] neg_lo:[0,1] neg_hi:[0,1]
	v_pk_add_f32 v[90:91], v[90:91], v[120:121] op_sel_hi:[1,0] neg_lo:[0,1] neg_hi:[0,1]
	v_pk_add_f32 v[92:93], v[92:93], v[120:121] op_sel_hi:[1,0] neg_lo:[0,1] neg_hi:[0,1]
	v_pk_add_f32 v[94:95], v[94:95], v[120:121] op_sel_hi:[1,0] neg_lo:[0,1] neg_hi:[0,1]
	v_sub_f32_e32 v79, v79, v120
	v_sub_f32_e32 v78, v78, v120
	v_sub_f32_e32 v77, v77, v120
	v_sub_f32_e32 v76, v76, v120
	v_sub_f32_e32 v75, v75, v120
	v_sub_f32_e32 v74, v74, v120
	v_sub_f32_e32 v73, v73, v120
	v_sub_f32_e32 v72, v72, v120
	v_sub_f32_e32 v71, v71, v120
	v_sub_f32_e32 v70, v70, v120
	v_sub_f32_e32 v69, v69, v120
	v_sub_f32_e32 v68, v68, v120
	v_sub_f32_e32 v67, v67, v120
	v_sub_f32_e32 v66, v66, v120
	v_sub_f32_e32 v65, v65, v120
	v_sub_f32_e32 v64, v64, v120
	v_cmp_gt_f32_e32 vcc, 1.0, v132
	s_cbranch_vccz .LBB0_164

.LBB0_171:
	s_mul_i32 s0, s35, 0x6000
	v_add_u32_e32 v80, s0, v161
	v_add_u32_e32 v156, v80, v162
	ds_read_b128 v[170:173], v156 offset:0
	ds_read_b128 v[174:177], v156 offset:0x3000
	v_add_u32_e32 v169, v80, v163
	ds_read_b128 v[178:181], v169 offset:0
	ds_read_b128 v[190:193], v169 offset:0x3000
	s_waitcnt lgkmcnt(2)
	v_xor_b32_e32 v64, 0x80000000, v167
	v_mov_b32_e32 v65, v64
	v_mov_b32_e32 v66, v64
	v_mov_b32_e32 v67, v64
	v_mov_b32_e32 v68, v64
	v_mov_b32_e32 v69, v64
	v_mov_b32_e32 v70, v64
	v_mov_b32_e32 v71, v64
	v_mov_b32_e32 v72, v64
	v_mov_b32_e32 v73, v64
	v_mov_b32_e32 v74, v64
	v_mov_b32_e32 v75, v64
	v_mov_b32_e32 v76, v64
	v_mov_b32_e32 v77, v64
	v_mov_b32_e32 v78, v64
	v_mov_b32_e32 v79, v64
	v_add_u32_e32 v182, v80, v164
	v_add_u32_e32 v183, v80, v165
	v_mfma_f32_32x32x16_bf16 v[80:95], v[170:173], v[96:99], v[64:79]
	ds_read_b128 v[170:173], v182 offset:0
	v_mfma_f32_32x32x16_bf16 v[64:79], v[174:177], v[96:99], v[64:79]
	ds_read_b128 v[174:177], v182 offset:0x3000
	s_waitcnt lgkmcnt(2)
	v_mfma_f32_32x32x16_bf16 v[80:95], v[178:181], v[100:103], v[80:95]
	ds_read_b128 v[178:181], v183 offset:0
	v_mfma_f32_32x32x16_bf16 v[64:79], v[190:193], v[100:103], v[64:79]
	ds_read_b128 v[190:193], v183 offset:0x3000
	s_waitcnt lgkmcnt(2)
	v_mfma_f32_32x32x16_bf16 v[80:95], v[170:173], v[104:107], v[80:95]
	ds_read_b128 v[170:173], v156 offset:0x80
	v_mfma_f32_32x32x16_bf16 v[64:79], v[174:177], v[104:107], v[64:79]
	ds_read_b128 v[174:177], v156 offset:0x3080
	s_waitcnt lgkmcnt(2)
	v_mfma_f32_32x32x16_bf16 v[80:95], v[178:181], v[108:111], v[80:95]
	ds_read_b128 v[178:181], v169 offset:0x80
	v_mfma_f32_32x32x16_bf16 v[64:79], v[190:193], v[108:111], v[64:79]
	ds_read_b128 v[190:193], v169 offset:0x3080
	s_waitcnt lgkmcnt(2)
	v_mfma_f32_32x32x16_bf16 v[80:95], v[170:173], v[112:115], v[80:95]
	ds_read_b128 v[170:173], v182 offset:0x80
	v_mfma_f32_32x32x16_bf16 v[64:79], v[174:177], v[112:115], v[64:79]
	ds_read_b128 v[174:177], v182 offset:0x3080
	s_waitcnt lgkmcnt(2)
	v_mfma_f32_32x32x16_bf16 v[80:95], v[178:181], v[116:119], v[80:95]
	ds_read_b128 v[178:181], v183 offset:0x80
	v_mfma_f32_32x32x16_bf16 v[64:79], v[190:193], v[116:119], v[64:79]
	ds_read_b128 v[190:193], v183 offset:0x3080
	s_waitcnt lgkmcnt(2)
	v_mfma_f32_32x32x16_bf16 v[80:95], v[170:173], v[120:123], v[80:95]
	ds_read_b128 v[170:173], v156 offset:0x100
	v_mfma_f32_32x32x16_bf16 v[64:79], v[174:177], v[120:123], v[64:79]
	ds_read_b128 v[174:177], v156 offset:0x3100
	s_waitcnt lgkmcnt(2)
	v_mfma_f32_32x32x16_bf16 v[80:95], v[178:181], v[124:127], v[80:95]
	ds_read_b128 v[178:181], v169 offset:0x100
	v_mfma_f32_32x32x16_bf16 v[64:79], v[190:193], v[124:127], v[64:79]
	ds_read_b128 v[190:193], v169 offset:0x3100
	s_waitcnt lgkmcnt(2)
	v_mfma_f32_32x32x16_bf16 v[80:95], v[170:173], v[128:131], v[80:95]
	ds_read_b128 v[170:173], v182 offset:0x100
	v_mfma_f32_32x32x16_bf16 v[64:79], v[174:177], v[128:131], v[64:79]
	ds_read_b128 v[174:177], v182 offset:0x3100
	s_waitcnt lgkmcnt(2)
	v_mfma_f32_32x32x16_bf16 v[80:95], v[178:181], v[132:135], v[80:95]
	ds_read_b128 v[178:181], v183 offset:0x100
	v_mfma_f32_32x32x16_bf16 v[64:79], v[190:193], v[132:135], v[64:79]
	ds_read_b128 v[190:193], v183 offset:0x3100
	s_waitcnt lgkmcnt(2)
	v_mfma_f32_32x32x16_bf16 v[80:95], v[170:173], v[136:139], v[80:95]
	s_waitcnt lgkmcnt(0)
	v_mfma_f32_32x32x16_bf16 v[64:79], v[174:177], v[136:139], v[64:79]
	v_mfma_f32_32x32x16_bf16 v[80:95], v[178:181], v[140:143], v[80:95]
	s_cmp_eq_u32 s31, 0
	s_cselect_b64 s[2:3], -1, 0
	s_cmp_lg_u32 s31, 0
	v_mfma_f32_32x32x16_bf16 v[64:79], v[190:193], v[140:143], v[64:79]
	s_nop 7
	v_max_f32_e32 v156, v80, v81
	v_max3_f32 v156, v156, v82, v83
	v_max3_f32 v156, v156, v84, v85
	v_max3_f32 v156, v156, v86, v87
	v_max3_f32 v156, v156, v88, v89
	v_max3_f32 v156, v156, v90, v91
	v_max3_f32 v156, v156, v92, v93
	v_max3_f32 v156, v156, v94, v95
	v_max3_f32 v156, v156, v64, v65
	v_max3_f32 v156, v156, v66, v67
	v_max3_f32 v156, v156, v68, v69
	v_max3_f32 v156, v156, v70, v71
	v_max3_f32 v156, v156, v72, v73
	v_max3_f32 v156, v156, v74, v75
	v_max3_f32 v156, v156, v76, v77
	v_max3_f32 v156, v156, v78, v79
	v_mov_b32_e32 v169, v156
	s_nop 1
	v_permlane32_swap_b32_e32 v156, v169
	v_max_f32_e32 v169, v156, v169
	s_cbranch_scc0 .LBB0_176
	v_cmp_ge_f32_e32 vcc, s62, v169
	s_cmp_lg_u64 vcc, exec
	s_mov_b64 s[24:25], 0
	s_mov_b64 s[22:23], 0
	s_cbranch_scc1 .LBB0_177
	v_mov_b32_e32 v169, 1.0
	s_branch .LBB0_183
